# norm loop: next item's two x rows prefetched into spare VGPRs (branch-free ctx/latent address select), counted waits so stores are never drained; row modulation batches for both rows issued before the
# baseline (speedup 1.0000x reference)
; DI const float* xsrc_row(const Params& p, int l, int b, int t) {
;   if (t < NCTX) return (l == 0 ? p.ctx : (const float*)(p.ws + WS_XRC)) + ((size_t)b * NCTX + t) * DM;
;   return (l == 0 ? p.x : (const float*)p.out) + ((size_t)b * NLAT + (t - NCTX)) * DM;
; DI void ph_norm(const Params& p, int l, int bid, int nb) {
;     ...
;   for (int it = bid; it < ROWS / 8; it += nb) {
;     float4 v[2][4];
;     const float* mod[2];
; #pragma unroll
;     for (int rr = 0; rr < 2; ++rr) {
;       const int row = it * 8 + rr * 4 + w;
;       const int b = row / NTOK, t = row % NTOK;
;       const float* src = xsrc_row(p, l, b, t);
;       mod[rr] = MOD + ((size_t)l * 9 + (t < NCTX ? 8 : b)) * 3072;
; #pragma unroll
;       for (int i = 0; i < 4; ++i) v[rr][i] = *(const float4*)(src + (i * 64 + lane) * 4);
;     }
.LBB0_115:
	s_waitcnt vmcnt(8) lgkmcnt(0)
	v_mov_b64_e32 v[24:25], v[220:221]
	v_mov_b64_e32 v[26:27], v[222:223]
	v_mov_b64_e32 v[12:13], v[224:225]
	v_mov_b64_e32 v[14:15], v[226:227]
	v_mov_b64_e32 v[4:5], v[228:229]
	v_mov_b64_e32 v[6:7], v[230:231]
	v_mov_b64_e32 v[0:1], v[232:233]
	v_mov_b64_e32 v[2:3], v[234:235]
	v_mov_b64_e32 v[28:29], v[236:237]
	v_mov_b64_e32 v[30:31], v[238:239]
	v_mov_b64_e32 v[20:21], v[240:241]
	v_mov_b64_e32 v[22:23], v[242:243]
	v_mov_b64_e32 v[16:17], v[244:245]
	v_mov_b64_e32 v[18:19], v[246:247]
	v_mov_b64_e32 v[8:9], v[248:249]
	v_mov_b64_e32 v[10:11], v[250:251]
	v_mul_hi_i32 v205, v44, s55
	v_lshrrev_b32_e32 v206, 31, v205
	v_ashrrev_i32_e32 v205, 9, v205
	v_add_u32_e32 v205, v205, v206
	v_mul_i32_i24_e32 v206, 0x900, v205
	v_sub_u32_e32 v206, v44, v206
	v_cmp_lt_i32_e32 vcc, s62, v206
	v_mov_b32_e32 v206, 8
	v_cndmask_b32_e32 v58, v206, v205, vcc
	v_add_u32_e32 v54, 4, v44
	v_mul_hi_i32 v205, v54, s55
	v_lshrrev_b32_e32 v206, 31, v205
	v_ashrrev_i32_e32 v205, 9, v205
	v_add_u32_e32 v205, v205, v206
	v_mul_i32_i24_e32 v206, 0x900, v205
	v_sub_u32_e32 v206, v54, v206
	v_cmp_lt_i32_e32 vcc, s62, v206
	v_mov_b32_e32 v206, 8
	v_cndmask_b32_e32 v56, v206, v205, vcc
	v_add_u32_e32 v45, s2, v58
	v_mov_b32_e32 v70, v25
	v_mov_b32_e32 v71, v13
	v_mov_b32_e32 v58, v24
	v_mov_b32_e32 v59, v12
	v_mov_b32_e32 v78, v5
	v_mov_b32_e32 v79, v1
	v_mul_hi_i32_i24_e32 v85, 0x3000, v45
	v_mul_i32_i24_e32 v84, 0x3000, v45
	v_pk_mul_f32 v[70:71], v[70:71], v[70:71]
	v_mov_b32_e32 v72, v26
	v_mov_b32_e32 v73, v14
	v_mov_b32_e32 v76, v4
	v_mov_b32_e32 v77, v0
	v_pk_mul_f32 v[78:79], v[78:79], v[78:79]
	v_lshl_add_u64 v[84:85], s[0:1], 0, v[84:85]
	v_pk_fma_f32 v[58:59], v[58:59], v[58:59], v[70:71]
	s_mov_b64 s[12:13], 0x1000
	v_mov_b32_e32 v74, v27
	v_mov_b32_e32 v75, v15
	v_mov_b32_e32 v80, v6
	v_mov_b32_e32 v81, v2
	v_pk_fma_f32 v[70:71], v[76:77], v[76:77], v[78:79]
	v_pk_fma_f32 v[58:59], v[72:73], v[72:73], v[58:59]
	v_lshl_add_u64 v[78:79], v[84:85], 0, s[12:13]
	v_mov_b32_e32 v82, v7
	v_mov_b32_e32 v83, v3
	v_pk_fma_f32 v[70:71], v[80:81], v[80:81], v[70:71]
	v_lshl_add_u64 v[80:81], v[84:85], 0, v[46:47]
	v_pk_fma_f32 v[58:59], v[74:75], v[74:75], v[58:59]
	v_lshl_add_u64 v[74:75], v[78:79], 0, v[46:47]
	v_mov_b64_e32 v[66:67], v[104:105]
	v_mov_b64_e32 v[68:69], v[106:107]
	v_pk_fma_f32 v[82:83], v[82:83], v[82:83], v[70:71]
	global_load_dwordx4 v[70:73], v[80:81], off
	global_load_dwordx4 v[120:123], v[80:81], off offset:1024
	global_load_dwordx4 v[124:127], v[80:81], off offset:2048
	global_load_dwordx4 v[128:131], v[80:81], off offset:3072
	s_nop 0
	global_load_dwordx4 v[132:135], v[74:75], off offset:1024
	global_load_dwordx4 v[136:139], v[74:75], off offset:2048
	global_load_dwordx4 v[140:143], v[74:75], off offset:3072
	global_load_dwordx4 v[74:77], v[74:75], off
	v_add_u32_e32 v204, s2, v56
	v_mul_hi_i32_i24_e32 v207, 0x3000, v204
	v_mul_i32_i24_e32 v206, 0x3000, v204
	v_lshl_add_u64 v[206:207], s[0:1], 0, v[206:207]
	v_lshl_add_u64 v[208:209], v[206:207], 0, v[46:47]
	v_lshl_add_u64 v[206:207], v[206:207], 0, s[12:13]
	v_lshl_add_u64 v[206:207], v[206:207], 0, v[46:47]
	global_load_dwordx4 v[212:215], v[208:209], off
	global_load_dwordx4 v[156:159], v[208:209], off offset:1024
	global_load_dwordx4 v[196:199], v[208:209], off offset:2048
	global_load_dwordx4 v[200:203], v[208:209], off offset:3072
	global_load_dwordx4 v[216:219], v[206:207], off
	global_load_dwordx4 v[144:147], v[206:207], off offset:1024
	global_load_dwordx4 v[148:151], v[206:207], off offset:2048
	global_load_dwordx4 v[152:155], v[206:207], off offset:3072
	v_readlane_b32 s8, v254, 11
	s_add_i32 s38, s10, s54
	s_cmpk_lt_i32 s38, 0x900
	s_nop 1
	s_cselect_b32 s8, s8, 0
	v_add_u32_e32 v204, s8, v44
	v_mul_hi_i32 v205, v204, s55
	v_lshrrev_b32_e32 v206, 31, v205
	v_ashrrev_i32_e32 v205, 9, v205
	v_add_u32_e32 v205, v205, v206
	v_mul_i32_i24_e32 v206, 0x900, v205
	v_sub_u32_e32 v206, v204, v206
	v_cmp_lt_i32_e32 vcc, s62, v206
	v_add_u32_e32 v207, 0xffffff00, v206
	v_lshlrev_b32_e32 v209, 20, v205
	v_cndmask_b32_e32 v206, v206, v207, vcc
	v_lshlrev_b32_e32 v207, 23, v205
	v_mov_b32_e32 v208, 8
	v_cndmask_b32_e32 v207, v209, v207, vcc
	v_cndmask_b32_e32 v210, v208, v205, vcc
	v_lshl_add_u32 v207, v206, 12, v207
	v_add_u32_e32 v207, v207, v46
	v_mov_b32_e32 v208, s4
	v_mov_b32_e32 v209, s5
	v_mov_b32_e32 v210, s6
	v_mov_b32_e32 v211, s7
	v_cndmask_b32_e32 v208, v208, v210, vcc
	v_cndmask_b32_e32 v209, v209, v211, vcc
	v_add_co_u32_e32 v208, vcc, v208, v207
	s_nop 1
	v_addc_co_u32_e32 v209, vcc, 0, v209, vcc
	global_load_dwordx4 v[220:223], v[208:209], off
	global_load_dwordx4 v[224:227], v[208:209], off offset:1024
	global_load_dwordx4 v[228:231], v[208:209], off offset:2048
	global_load_dwordx4 v[232:235], v[208:209], off offset:3072
	v_add_u32_e32 v204, 4, v204
	v_mul_hi_i32 v205, v204, s55
	v_lshrrev_b32_e32 v206, 31, v205
	v_ashrrev_i32_e32 v205, 9, v205
	v_add_u32_e32 v205, v205, v206
	v_mul_i32_i24_e32 v206, 0x900, v205
	v_sub_u32_e32 v206, v204, v206
	v_cmp_lt_i32_e32 vcc, s62, v206
	v_add_u32_e32 v207, 0xffffff00, v206
	v_lshlrev_b32_e32 v209, 20, v205
	v_cndmask_b32_e32 v206, v206, v207, vcc
	v_lshlrev_b32_e32 v207, 23, v205
	v_mov_b32_e32 v208, 8
	v_cndmask_b32_e32 v207, v209, v207, vcc
	v_cndmask_b32_e32 v210, v208, v205, vcc
	v_lshl_add_u32 v207, v206, 12, v207
	v_add_u32_e32 v207, v207, v46
	v_mov_b32_e32 v208, s4
	v_mov_b32_e32 v209, s5
	v_mov_b32_e32 v210, s6
	v_mov_b32_e32 v211, s7
	v_cndmask_b32_e32 v208, v208, v210, vcc
	v_cndmask_b32_e32 v209, v209, v211, vcc
	v_add_co_u32_e32 v208, vcc, v208, v207
	s_nop 1
; DI size_t kblk(int row, int col, int nrows) { return ((size_t)(col >> 5) * nrows + row) * 32 + (col & 31); }
; DI unsigned pk2(float a, float b) { hwf32x2 f = {a, b}; hwbf16x2 r = __builtin_convertvector(f, hwbf16x2); return __builtin_bit_cast(unsigned, r); }
; DI void ph_norm(const Params& p, int l, int bid, int nb) {
;     ...
; #pragma unroll
;     for (int rr = 0; rr < 2; ++rr) {
;       const int row = it * 8 + rr * 4 + w;
;       float ss = 0.f;
; #pragma unroll
;       for (int i = 0; i < 4; ++i) ss += v[rr][i].x * v[rr][i].x + v[rr][i].y * v[rr][i].y + v[rr][i].z * v[rr][i].z + v[rr][i].w * v[rr][i].w;
;       ss = wave_sum(ss);
;       const float rstd = rsqrtf(ss * (1.f / DM) + EPS);
; #pragma unroll
;       for (int i = 0; i < 4; ++i) {
;         const int j = (i * 64 + lane) * 4;
;         const float4 gg = *(const float4*)(g + j);
;         const float4 sh = *(const float4*)(mod[rr] + j);
;         const float4 sc = *(const float4*)(mod[rr] + 1024 + j);
;         uint2 o;
;         o.x = pk2(v[rr][i].x * rstd * gg.x * (1.f + sc.x) + sh.x, v[rr][i].y * rstd * gg.y * (1.f + sc.y) + sh.y);
;         o.y = pk2(v[rr][i].z * rstd * gg.z * (1.f + sc.z) + sh.z, v[rr][i].w * rstd * gg.w * (1.f + sc.w) + sh.w);
;         *(uint2*)(H + kblk(row, j, ROWS)) = o;
	v_addc_co_u32_e32 v209, vcc, 0, v209, vcc
	global_load_dwordx4 v[236:239], v[208:209], off
	global_load_dwordx4 v[240:243], v[208:209], off offset:1024
	global_load_dwordx4 v[244:247], v[208:209], off offset:2048
	global_load_dwordx4 v[248:251], v[208:209], off offset:3072
	v_mov_b32_e32 v85, v58
	v_mov_b32_e32 v87, v82
	s_mov_b32 s8, 0x3a800000
	v_ashrrev_i32_e32 v45, 31, v44
	s_add_i32 s10, s10, s54
	s_mov_b32 s38, 0x800000
	s_cmpk_lt_i32 s10, 0x900
	v_mov_b32_e32 v94, v29
	v_mov_b32_e32 v95, v21
	v_mov_b32_e32 v92, v28
	v_mov_b32_e32 v93, v20
	v_mov_b32_e32 v102, v17
	v_mov_b32_e32 v103, v9
	v_pk_mul_f32 v[94:95], v[94:95], v[94:95]
	v_mov_b32_e32 v88, v30
	v_mov_b32_e32 v89, v22
	v_mov_b32_e32 v100, v16
	v_mov_b32_e32 v101, v8
	v_pk_mul_f32 v[102:103], v[102:103], v[102:103]
	v_pk_fma_f32 v[92:93], v[92:93], v[92:93], v[94:95]
	v_mov_b32_e32 v90, v31
	v_mov_b32_e32 v91, v23
	v_mov_b32_e32 v96, v18
	v_mov_b32_e32 v97, v10
	v_pk_fma_f32 v[94:95], v[100:101], v[100:101], v[102:103]
	v_pk_fma_f32 v[88:89], v[88:89], v[88:89], v[92:93]
	v_mov_b32_e32 v98, v19
	v_mov_b32_e32 v99, v11
	v_pk_fma_f32 v[92:93], v[96:97], v[96:97], v[94:95]
	v_pk_fma_f32 v[88:89], v[90:91], v[90:91], v[88:89]
	v_pk_fma_f32 v[90:91], v[98:99], v[98:99], v[92:93]
	v_mov_b32_e32 v84, v88
	v_mov_b32_e32 v58, v89
	v_mov_b32_e32 v86, v90
	v_pk_add_f32 v[58:59], v[84:85], v[58:59]
	v_mov_b32_e32 v82, v91
	v_pk_add_f32 v[58:59], v[58:59], v[86:87]
	v_lshl_add_u64 v[84:85], v[44:45], 0, v[36:37]
	v_pk_add_f32 v[58:59], v[58:59], v[82:83]
	v_mov_b32_e32 v82, v58
	v_mov_b32_e32 v83, v59
	v_lshlrev_b64 v[84:85], 6, v[84:85]
	v_lshl_add_u64 v[84:85], v[32:33], 0, v[84:85]
	v_permlane32_swap_b32_e32 v82, v58
	v_permlane32_swap_b32_e32 v83, v59
	v_pk_add_f32 v[58:59], v[58:59], v[82:83]
	v_mov_b32_e32 v82, v58
	v_mov_b32_e32 v83, v59
	s_nop 1
	v_permlane16_swap_b32_e32 v82, v58
	v_permlane16_swap_b32_e32 v83, v59
	v_pk_add_f32 v[58:59], v[58:59], v[82:83]
	s_nop 1
	v_add_f32_dpp v58, v58, v58 row_ror:8 row_mask:0xf bank_mask:0xf
	v_add_f32_dpp v59, v59, v59 row_ror:8 row_mask:0xf bank_mask:0xf
	s_nop 0
	v_add_f32_dpp v82, v58, v58 row_shl:4 row_mask:0xf bank_mask:0x5
	v_add_f32_dpp v83, v59, v59 row_shl:4 row_mask:0xf bank_mask:0x5
	v_add_f32_dpp v82, v58, v58 row_shr:4 row_mask:0xf bank_mask:0xa
	v_add_f32_dpp v83, v59, v59 row_shr:4 row_mask:0xf bank_mask:0xa
	s_nop 0
	v_add_f32_dpp v58, v82, v82 quad_perm:[2,3,0,1] row_mask:0xf bank_mask:0xf
	v_add_f32_dpp v59, v83, v83 quad_perm:[2,3,0,1] row_mask:0xf bank_mask:0xf
	s_nop 0
	v_add_f32_dpp v58, v58, v58 quad_perm:[1,0,3,2] row_mask:0xf bank_mask:0xf
	v_add_f32_dpp v59, v59, v59 quad_perm:[1,0,3,2] row_mask:0xf bank_mask:0xf
	s_waitcnt vmcnt(8)
	v_pk_add_f32 v[74:75], v[74:75], 1.0 op_sel_hi:[1,0]
	v_pk_add_f32 v[76:77], v[76:77], 1.0 op_sel_hi:[1,0]
	s_nop 0
	v_pk_fma_f32 v[58:59], v[58:59], s[8:9], v[162:163] op_sel_hi:[1,0,0]
	s_mov_b32 s8, 0x800000
	v_mul_f32_e32 v55, 0x4b800000, v59
	v_cmp_gt_f32_e32 vcc, s8, v59
	v_lshl_add_u64 v[82:83], v[78:79], 0, v[48:49]
	s_nop 0
	v_cndmask_b32_e32 v55, v59, v55, vcc
	v_rsq_f32_e32 v55, v55
	s_nop 0
	v_mul_f32_e32 v57, 0x45800000, v55
	v_cndmask_b32_e32 v86, v55, v57, vcc
	v_pk_mul_f32 v[24:25], v[24:25], v[86:87] op_sel_hi:[1,0]
	v_pk_mul_f32 v[26:27], v[26:27], v[86:87] op_sel_hi:[1,0]
	v_pk_mul_f32 v[24:25], v[66:67], v[24:25]
	v_pk_mul_f32 v[26:27], v[68:69], v[26:27]
	v_pk_fma_f32 v[24:25], v[74:75], v[24:25], v[70:71]
	v_pk_fma_f32 v[26:27], v[26:27], v[76:77], v[72:73]
	v_cvt_pk_bf16_f32 v24, v24, v25
	v_cvt_pk_bf16_f32 v25, v26, v27
	global_store_dwordx2 v[84:85], v[24:25], off
	v_mov_b64_e32 v[24:25], v[108:109]
	v_mov_b64_e32 v[26:27], v[110:111]
	s_nop 0
	v_mov_b64_e32 v[66:67], v[132:133]
	v_mov_b64_e32 v[68:69], v[134:135]
	v_mov_b64_e32 v[70:71], v[120:121]
	v_mov_b64_e32 v[72:73], v[122:123]
	v_pk_mul_f32 v[12:13], v[12:13], v[86:87] op_sel_hi:[1,0]
	v_pk_mul_f32 v[14:15], v[14:15], v[86:87] op_sel_hi:[1,0]
	v_lshl_add_u64 v[74:75], v[44:45], 0, v[38:39]
	v_lshlrev_b64 v[74:75], 6, v[74:75]
	v_lshl_add_u64 v[74:75], v[32:33], 0, v[74:75]
	v_lshl_add_u64 v[76:77], v[78:79], 0, v[50:51]
	v_pk_mul_f32 v[4:5], v[4:5], v[86:87] op_sel_hi:[1,0]
	v_pk_mul_f32 v[6:7], v[6:7], v[86:87] op_sel_hi:[1,0]
	v_pk_mul_f32 v[0:1], v[0:1], v[86:87] op_sel_hi:[1,0]
	v_pk_mul_f32 v[2:3], v[2:3], v[86:87] op_sel_hi:[1,0]
	v_add_u32_e32 v55, s2, v56
	v_mul_hi_i32_i24_e32 v57, 0x3000, v55
	v_mul_i32_i24_e32 v56, 0x3000, v55
	v_lshl_add_u64 v[56:57], s[0:1], 0, v[56:57]
	v_cmp_gt_f32_e32 vcc, s8, v58
	v_ashrrev_i32_e32 v55, 31, v54
	v_readlane_b32 s8, v254, 11
	v_pk_mul_f32 v[12:13], v[12:13], v[24:25]
	s_waitcnt lgkmcnt(0)
	v_pk_add_f32 v[24:25], v[66:67], 1.0 op_sel_hi:[1,0]
	v_pk_mul_f32 v[14:15], v[14:15], v[26:27]
	v_pk_add_f32 v[26:27], v[68:69], 1.0 op_sel_hi:[1,0]
	v_pk_fma_f32 v[12:13], v[12:13], v[24:25], v[70:71]
	v_pk_fma_f32 v[14:15], v[14:15], v[26:27], v[72:73]
	v_cvt_pk_bf16_f32 v12, v12, v13
	v_cvt_pk_bf16_f32 v13, v14, v15
	global_store_dwordx2 v[74:75], v[12:13], off
	v_mov_b64_e32 v[12:13], v[112:113]
	v_mov_b64_e32 v[14:15], v[114:115]
	s_nop 0
	v_mov_b64_e32 v[24:25], v[136:137]
	v_mov_b64_e32 v[26:27], v[138:139]
	v_mov_b64_e32 v[66:67], v[124:125]
	v_mov_b64_e32 v[68:69], v[126:127]
	v_lshl_add_u64 v[70:71], v[44:45], 0, v[40:41]
	v_lshlrev_b64 v[70:71], 6, v[70:71]
	v_lshl_add_u64 v[70:71], v[32:33], 0, v[70:71]
	v_lshl_add_u64 v[72:73], v[78:79], 0, v[52:53]
	v_pk_mul_f32 v[4:5], v[4:5], v[12:13]
	s_waitcnt lgkmcnt(0)
; DI size_t kblk(int row, int col, int nrows) { return ((size_t)(col >> 5) * nrows + row) * 32 + (col & 31); }
; DI unsigned pk2(float a, float b) { hwf32x2 f = {a, b}; hwbf16x2 r = __builtin_convertvector(f, hwbf16x2); return __builtin_bit_cast(unsigned, r); }
; DI void ph_norm(const Params& p, int l, int bid, int nb) {
;     ...
; #pragma unroll
;       for (int i = 0; i < 4; ++i) {
;         const int j = (i * 64 + lane) * 4;
;         const float4 gg = *(const float4*)(g + j);
;         const float4 sh = *(const float4*)(mod[rr] + j);
;         const float4 sc = *(const float4*)(mod[rr] + 1024 + j);
;         uint2 o;
;         o.x = pk2(v[rr][i].x * rstd * gg.x * (1.f + sc.x) + sh.x, v[rr][i].y * rstd * gg.y * (1.f + sc.y) + sh.y);
;         o.y = pk2(v[rr][i].z * rstd * gg.z * (1.f + sc.z) + sh.z, v[rr][i].w * rstd * gg.w * (1.f + sc.w) + sh.w);
;         *(uint2*)(H + kblk(row, j, ROWS)) = o;
	v_pk_add_f32 v[12:13], v[24:25], 1.0 op_sel_hi:[1,0]
	v_pk_mul_f32 v[6:7], v[6:7], v[14:15]
	v_pk_add_f32 v[14:15], v[26:27], 1.0 op_sel_hi:[1,0]
	v_pk_fma_f32 v[4:5], v[4:5], v[12:13], v[66:67]
	v_pk_fma_f32 v[6:7], v[6:7], v[14:15], v[68:69]
	v_cvt_pk_bf16_f32 v4, v4, v5
	v_cvt_pk_bf16_f32 v5, v6, v7
	global_store_dwordx2 v[70:71], v[4:5], off
	v_mov_b64_e32 v[4:5], v[116:117]
	v_mov_b64_e32 v[6:7], v[118:119]
	s_nop 0
	v_mov_b64_e32 v[12:13], v[140:141]
	v_mov_b64_e32 v[14:15], v[142:143]
	v_mov_b64_e32 v[24:25], v[128:129]
	v_mov_b64_e32 v[26:27], v[130:131]
	v_lshl_add_u64 v[66:67], v[44:45], 0, v[42:43]
	v_lshlrev_b64 v[66:67], 6, v[66:67]
	v_lshl_add_u64 v[66:67], v[32:33], 0, v[66:67]
	v_lshl_add_u64 v[68:69], v[56:57], 0, s[12:13]
	v_lshl_add_u64 v[70:71], v[68:69], 0, v[46:47]
	v_mul_f32_e32 v45, 0x4b800000, v58
	v_cndmask_b32_e32 v45, v58, v45, vcc
	v_rsq_f32_e32 v45, v45
	v_add_u32_e32 v44, s8, v44
	v_mul_f32_e32 v58, 0x45800000, v45
	v_cndmask_b32_e32 v58, v45, v58, vcc
	v_pk_mul_f32 v[28:29], v[28:29], v[58:59] op_sel_hi:[1,0]
	v_pk_mul_f32 v[30:31], v[30:31], v[58:59] op_sel_hi:[1,0]
	v_pk_mul_f32 v[20:21], v[20:21], v[58:59] op_sel_hi:[1,0]
	v_pk_mul_f32 v[22:23], v[22:23], v[58:59] op_sel_hi:[1,0]
	v_pk_mul_f32 v[16:17], v[16:17], v[58:59] op_sel_hi:[1,0]
	v_pk_mul_f32 v[18:19], v[18:19], v[58:59] op_sel_hi:[1,0]
	v_pk_mul_f32 v[8:9], v[8:9], v[58:59] op_sel_hi:[1,0]
	v_pk_mul_f32 v[10:11], v[10:11], v[58:59] op_sel_hi:[1,0]
	v_pk_mul_f32 v[0:1], v[0:1], v[4:5]
	s_waitcnt lgkmcnt(0)
	v_pk_add_f32 v[4:5], v[12:13], 1.0 op_sel_hi:[1,0]
	v_pk_mul_f32 v[2:3], v[2:3], v[6:7]
	v_pk_add_f32 v[6:7], v[14:15], 1.0 op_sel_hi:[1,0]
	v_pk_fma_f32 v[0:1], v[0:1], v[4:5], v[24:25]
	v_pk_fma_f32 v[2:3], v[2:3], v[6:7], v[26:27]
	v_cvt_pk_bf16_f32 v0, v0, v1
	v_cvt_pk_bf16_f32 v1, v2, v3
	global_store_dwordx2 v[66:67], v[0:1], off
	v_mov_b64_e32 v[0:1], v[104:105]
	v_mov_b64_e32 v[2:3], v[106:107]
	s_nop 0
	v_mov_b64_e32 v[4:5], v[216:217]
	v_mov_b64_e32 v[6:7], v[218:219]
	v_lshl_add_u64 v[24:25], v[56:57], 0, v[46:47]
	v_mov_b64_e32 v[12:13], v[212:213]
	v_mov_b64_e32 v[14:15], v[214:215]
	v_lshl_add_u64 v[26:27], v[54:55], 0, v[36:37]
	v_lshlrev_b64 v[26:27], 6, v[26:27]
	v_lshl_add_u64 v[26:27], v[32:33], 0, v[26:27]
	v_lshl_add_u64 v[56:57], v[68:69], 0, v[48:49]
	v_pk_mul_f32 v[0:1], v[0:1], v[28:29]
	s_waitcnt lgkmcnt(0)
	v_pk_add_f32 v[4:5], v[4:5], 1.0 op_sel_hi:[1,0]
	v_pk_mul_f32 v[2:3], v[2:3], v[30:31]
	v_pk_add_f32 v[6:7], v[6:7], 1.0 op_sel_hi:[1,0]
	v_pk_fma_f32 v[0:1], v[4:5], v[0:1], v[12:13]
	v_pk_fma_f32 v[2:3], v[2:3], v[6:7], v[14:15]
	v_cvt_pk_bf16_f32 v0, v0, v1
	v_cvt_pk_bf16_f32 v1, v2, v3
	global_store_dwordx2 v[26:27], v[0:1], off
	v_mov_b64_e32 v[0:1], v[108:109]
	v_mov_b64_e32 v[2:3], v[110:111]
	s_nop 0
	v_mov_b64_e32 v[4:5], v[144:145]
	v_mov_b64_e32 v[6:7], v[146:147]
	v_mov_b64_e32 v[12:13], v[156:157]
	v_mov_b64_e32 v[14:15], v[158:159]
	v_lshl_add_u64 v[26:27], v[54:55], 0, v[38:39]
	v_lshlrev_b64 v[26:27], 6, v[26:27]
	v_lshl_add_u64 v[26:27], v[32:33], 0, v[26:27]
	v_lshl_add_u64 v[28:29], v[68:69], 0, v[50:51]
	v_pk_mul_f32 v[0:1], v[20:21], v[0:1]
	s_waitcnt lgkmcnt(0)
	v_pk_add_f32 v[4:5], v[4:5], 1.0 op_sel_hi:[1,0]
	v_pk_mul_f32 v[2:3], v[22:23], v[2:3]
	v_pk_add_f32 v[6:7], v[6:7], 1.0 op_sel_hi:[1,0]
	v_pk_fma_f32 v[0:1], v[0:1], v[4:5], v[12:13]
	v_pk_fma_f32 v[2:3], v[2:3], v[6:7], v[14:15]
	v_cvt_pk_bf16_f32 v0, v0, v1
	v_cvt_pk_bf16_f32 v1, v2, v3
	global_store_dwordx2 v[26:27], v[0:1], off
	v_mov_b64_e32 v[0:1], v[112:113]
	v_mov_b64_e32 v[2:3], v[114:115]
	s_nop 0
	v_mov_b64_e32 v[4:5], v[148:149]
	v_mov_b64_e32 v[6:7], v[150:151]
	v_mov_b64_e32 v[12:13], v[196:197]
	v_mov_b64_e32 v[14:15], v[198:199]
	v_lshl_add_u64 v[20:21], v[54:55], 0, v[40:41]
	v_lshlrev_b64 v[20:21], 6, v[20:21]
	v_lshl_add_u64 v[20:21], v[32:33], 0, v[20:21]
	v_lshl_add_u64 v[22:23], v[68:69], 0, v[52:53]
	v_pk_mul_f32 v[0:1], v[16:17], v[0:1]
	s_waitcnt lgkmcnt(0)
	v_pk_add_f32 v[4:5], v[4:5], 1.0 op_sel_hi:[1,0]
	v_pk_mul_f32 v[2:3], v[18:19], v[2:3]
	v_pk_add_f32 v[6:7], v[6:7], 1.0 op_sel_hi:[1,0]
	v_pk_fma_f32 v[0:1], v[0:1], v[4:5], v[12:13]
	v_pk_fma_f32 v[2:3], v[2:3], v[6:7], v[14:15]
	v_cvt_pk_bf16_f32 v0, v0, v1
	v_cvt_pk_bf16_f32 v1, v2, v3
	global_store_dwordx2 v[20:21], v[0:1], off
	v_mov_b64_e32 v[0:1], v[116:117]
	v_mov_b64_e32 v[2:3], v[118:119]
	s_nop 0
	v_mov_b64_e32 v[4:5], v[152:153]
	v_mov_b64_e32 v[6:7], v[154:155]
	v_mov_b64_e32 v[12:13], v[200:201]
	v_mov_b64_e32 v[14:15], v[202:203]
	v_lshl_add_u64 v[16:17], v[54:55], 0, v[42:43]
	v_lshlrev_b64 v[16:17], 6, v[16:17]
	v_lshl_add_u64 v[16:17], v[32:33], 0, v[16:17]
	v_pk_mul_f32 v[0:1], v[8:9], v[0:1]
	s_waitcnt lgkmcnt(0)
	v_pk_add_f32 v[4:5], v[4:5], 1.0 op_sel_hi:[1,0]
	v_pk_mul_f32 v[2:3], v[10:11], v[2:3]
	v_pk_add_f32 v[6:7], v[6:7], 1.0 op_sel_hi:[1,0]
	v_pk_fma_f32 v[0:1], v[0:1], v[4:5], v[12:13]
	v_pk_fma_f32 v[2:3], v[2:3], v[6:7], v[14:15]
	v_cvt_pk_bf16_f32 v0, v0, v1
	v_cvt_pk_bf16_f32 v1, v2, v3
	global_store_dwordx2 v[16:17], v[0:1], off
	s_cbranch_scc0 .LBB0_124
	s_branch .LBB0_115
; DI const float* xsrc_row(const Params& p, int l, int b, int t) {
;   if (t < NCTX) return (l == 0 ? p.ctx : (const float*)(p.ws + WS_XRC)) + ((size_t)b * NCTX + t) * DM;
;   return (l == 0 ? p.x : (const float*)p.out) + ((size_t)b * NLAT + (t - NCTX)) * DM;
; DI void ph_norm(const Params& p, int l, int bid, int nb) {
;     ...
;       const int row = it * 8 + rr * 4 + w;
;       const int b = row / NTOK, t = row % NTOK;
;       const float* src = xsrc_row(p, l, b, t);
;       mod[rr] = MOD + ((size_t)l * 9 + (t < NCTX ? 8 : b)) * 3072;
; #pragma unroll
;       for (int i = 0; i < 4; ++i) v[rr][i] = *(const float4*)(src + (i * 64 + lane) * 4);
.LBB0_116:
	v_mov_b32_e32 v204, v44
	v_mul_hi_i32 v205, v204, s55
	v_lshrrev_b32_e32 v206, 31, v205
	v_ashrrev_i32_e32 v205, 9, v205
	v_add_u32_e32 v205, v205, v206
	v_mul_i32_i24_e32 v206, 0x900, v205
	v_sub_u32_e32 v206, v204, v206
	v_cmp_lt_i32_e32 vcc, s62, v206
	v_add_u32_e32 v207, 0xffffff00, v206
	v_lshlrev_b32_e32 v209, 20, v205
	v_cndmask_b32_e32 v206, v206, v207, vcc
	v_lshlrev_b32_e32 v207, 23, v205
	v_mov_b32_e32 v208, 8
	v_cndmask_b32_e32 v207, v209, v207, vcc
	v_cndmask_b32_e32 v210, v208, v205, vcc
	v_lshl_add_u32 v207, v206, 12, v207
	v_add_u32_e32 v207, v207, v46
	v_mov_b32_e32 v208, s4
	v_mov_b32_e32 v209, s5
	v_mov_b32_e32 v210, s6
	v_mov_b32_e32 v211, s7
	v_cndmask_b32_e32 v208, v208, v210, vcc
	v_cndmask_b32_e32 v209, v209, v211, vcc
	v_add_co_u32_e32 v208, vcc, v208, v207
	s_nop 1
	v_addc_co_u32_e32 v209, vcc, 0, v209, vcc
	global_load_dwordx4 v[220:223], v[208:209], off
	global_load_dwordx4 v[224:227], v[208:209], off offset:1024
	global_load_dwordx4 v[228:231], v[208:209], off offset:2048
	global_load_dwordx4 v[232:235], v[208:209], off offset:3072
	v_add_u32_e32 v204, 4, v204
	v_mul_hi_i32 v205, v204, s55
	v_lshrrev_b32_e32 v206, 31, v205
	v_ashrrev_i32_e32 v205, 9, v205
	v_add_u32_e32 v205, v205, v206
	v_mul_i32_i24_e32 v206, 0x900, v205
	v_sub_u32_e32 v206, v204, v206
	v_cmp_lt_i32_e32 vcc, s62, v206
	v_add_u32_e32 v207, 0xffffff00, v206
	v_lshlrev_b32_e32 v209, 20, v205
	v_cndmask_b32_e32 v206, v206, v207, vcc
	v_lshlrev_b32_e32 v207, 23, v205
	v_mov_b32_e32 v208, 8
	v_cndmask_b32_e32 v207, v209, v207, vcc
	v_cndmask_b32_e32 v210, v208, v205, vcc
	v_lshl_add_u32 v207, v206, 12, v207
	v_add_u32_e32 v207, v207, v46
	v_mov_b32_e32 v208, s4
	v_mov_b32_e32 v209, s5
	v_mov_b32_e32 v210, s6
	v_mov_b32_e32 v211, s7
	v_cndmask_b32_e32 v208, v208, v210, vcc
	v_cndmask_b32_e32 v209, v209, v211, vcc
	v_add_co_u32_e32 v208, vcc, v208, v207
	s_nop 1
	v_addc_co_u32_e32 v209, vcc, 0, v209, vcc
	global_load_dwordx4 v[236:239], v[208:209], off
	global_load_dwordx4 v[240:243], v[208:209], off offset:1024
	global_load_dwordx4 v[244:247], v[208:209], off offset:2048
	global_load_dwordx4 v[248:251], v[208:209], off offset:3072
	s_waitcnt vmcnt(0)
	s_branch .LBB0_115
